# v014 + P1/P3 QKV epilogue VALU stream rewritten by hand: lane-pair exchange with one v_cndmask_b32_dpp per output dword (was select + mov0 + mov_dpp + 2 selects), store addresses stepped by 8 rows wit
# baseline (speedup 1.0000x reference)
; __device__ __forceinline__ unsigned cvt_pk_bf16(float lo, float hi) { const cvt_f32x2_t v = {lo, hi}; const cvt_bf16x2_t b = __builtin_convertvector(v, cvt_bf16x2_t); return __builtin_bit_cast(unsigned, b); }
; __device__ __forceinline__ unsigned swap8(unsigned v) { return (unsigned)__builtin_amdgcn_update_dpp(0, (int)v, 0x128  , 0xF, 0xF, false); }
; __device__ __forceinline__ void wide_store(bf16_t* O, int ldc, int rowg  , int col0  , int fr, u32x4 w0, u32x4 w1) {
;     const bool lo = fr < 8;
;     u32x4 snd = lo ? w1 : w0, rcv;
;     rcv.x = swap8(snd.x); rcv.y = swap8(snd.y); rcv.z = swap8(snd.z); rcv.w = swap8(snd.w);
;     const u32x4 first = lo ? w0 : rcv, second = lo ? rcv : w1;
;     bf16_t* p = O + (size_t)(rowg + (fr & 7)) * ldc + col0 + (lo ? 0 : 32);
;     __builtin_nontemporal_store(first, (u32x4*)p); __builtin_nontemporal_store(second, (u32x4*)(p + (size_t)8 * ldc));
; }
;     __device__ __forceinline__ void operator()(const f32x4 (&acc)[2][2][4][2], const Unit& u, int wr, int wc, int fr, int fq) const {
;         const int col0 = u.pn * BM + wc * 64 + 8 * fq;
; #pragma unroll
;         for (int ai = 0; ai < 2; ++ai)
; #pragma unroll
;             for (int m = 0; m < 4; ++m) { const int rowg = u.pm * BM + ai * HALF + wr * 64 + m * 16;
;                 const float sc = slots ? rstd_from_slots(slots, rowg + fr, fq) : 1.0f;
;                 u32x4 w[2];
; #pragma unroll
;                 for (int bj = 0; bj < 2; ++bj) { const f32x4 v0 = acc[ai][bj][m][0] * sc, v1 = acc[ai][bj][m][1] * sc;
;                     w[bj].x = cvt_pk_bf16(v0[0], v0[1]); w[bj].y = cvt_pk_bf16(v0[2], v0[3]); w[bj].z = cvt_pk_bf16(v1[0], v1[1]); w[bj].w = cvt_pk_bf16(v1[2], v1[3]); }
;                 wide_store(O, ldc, rowg, col0, fr, w[0], w[1]); }
.LBB0_218:
	v_readlane_b32 s30, v239, 49
	v_readlane_b32 s31, v239, 50
	s_lshl_b32 s0, s0, 8
	v_lshl_or_b32 v162, s1, 8, v147
	v_add_u32_e32 v164, s0, v148
	v_ashrrev_i32_e32 v163, 31, v162
	s_mov_b32 s98, 0x24000
	s_mov_b32 s99, 0
	v_lshlrev_b64 v[162:163], 1, v[162:163]
	v_mov_b64_e32 v[168:169], s[30:31]
	v_mad_i64_i32 v[164:165], s[20:21], v164, s53, v[168:169]
	v_lshl_add_u64 v[162:163], v[162:163], 0, v[136:137]
	v_lshl_add_u64 v[164:165], v[164:165], 0, v[162:163]
	v_cvt_pk_bf16_f32 v124, v124, v125
	v_cvt_pk_bf16_f32 v125, v126, v127
	v_cvt_pk_bf16_f32 v126, v120, v121
	v_cvt_pk_bf16_f32 v127, v122, v123
	v_cvt_pk_bf16_f32 v116, v116, v117
	v_cvt_pk_bf16_f32 v117, v118, v119
	v_cvt_pk_bf16_f32 v118, v112, v113
	v_cvt_pk_bf16_f32 v119, v114, v115
	v_cvt_pk_bf16_f32 v108, v108, v109
	v_cvt_pk_bf16_f32 v109, v110, v111
	v_cvt_pk_bf16_f32 v110, v104, v105
	v_cvt_pk_bf16_f32 v111, v106, v107
	v_cvt_pk_bf16_f32 v100, v100, v101
	v_cvt_pk_bf16_f32 v101, v102, v103
	v_cvt_pk_bf16_f32 v102, v96, v97
	v_cvt_pk_bf16_f32 v103, v98, v99
	s_not_b64 vcc, s[2:3]
	v_cndmask_b32_dpp v112, v124, v116, vcc row_ror:8 row_mask:0xf bank_mask:0xf
	v_cndmask_b32_dpp v113, v125, v117, vcc row_ror:8 row_mask:0xf bank_mask:0xf
	v_cndmask_b32_dpp v114, v126, v118, vcc row_ror:8 row_mask:0xf bank_mask:0xf
	v_cndmask_b32_dpp v115, v127, v119, vcc row_ror:8 row_mask:0xf bank_mask:0xf
	v_cndmask_b32_dpp v96, v108, v100, vcc row_ror:8 row_mask:0xf bank_mask:0xf
	v_cndmask_b32_dpp v97, v109, v101, vcc row_ror:8 row_mask:0xf bank_mask:0xf
	v_cndmask_b32_dpp v98, v110, v102, vcc row_ror:8 row_mask:0xf bank_mask:0xf
	v_cndmask_b32_dpp v99, v111, v103, vcc row_ror:8 row_mask:0xf bank_mask:0xf
	s_mov_b64 vcc, s[2:3]
	v_cndmask_b32_dpp v120, v116, v124, vcc row_ror:8 row_mask:0xf bank_mask:0xf
	v_cndmask_b32_dpp v121, v117, v125, vcc row_ror:8 row_mask:0xf bank_mask:0xf
	v_cndmask_b32_dpp v122, v118, v126, vcc row_ror:8 row_mask:0xf bank_mask:0xf
	v_cndmask_b32_dpp v123, v119, v127, vcc row_ror:8 row_mask:0xf bank_mask:0xf
	v_cndmask_b32_dpp v104, v100, v108, vcc row_ror:8 row_mask:0xf bank_mask:0xf
	v_cndmask_b32_dpp v105, v101, v109, vcc row_ror:8 row_mask:0xf bank_mask:0xf
	v_cndmask_b32_dpp v106, v102, v110, vcc row_ror:8 row_mask:0xf bank_mask:0xf
	v_cndmask_b32_dpp v107, v103, v111, vcc row_ror:8 row_mask:0xf bank_mask:0xf
	global_store_dwordx4 v[164:165], v[120:123], off nt
	v_lshl_add_u64 v[166:167], v[164:165], 0, s[98:99]
	global_store_dwordx4 v[166:167], v[112:115], off nt
	v_lshl_add_u64 v[164:165], v[166:167], 0, s[98:99]
	global_store_dwordx4 v[164:165], v[104:107], off nt
	v_lshl_add_u64 v[166:167], v[164:165], 0, s[98:99]
	global_store_dwordx4 v[166:167], v[96:99], off nt
	v_cvt_pk_bf16_f32 v92, v92, v93
	v_cvt_pk_bf16_f32 v93, v94, v95
	v_cvt_pk_bf16_f32 v94, v88, v89
	v_cvt_pk_bf16_f32 v95, v90, v91
	v_cvt_pk_bf16_f32 v84, v84, v85
	v_cvt_pk_bf16_f32 v85, v86, v87
	v_cvt_pk_bf16_f32 v86, v80, v81
	v_cvt_pk_bf16_f32 v87, v82, v83
	v_cvt_pk_bf16_f32 v76, v76, v77
	v_cvt_pk_bf16_f32 v77, v78, v79
	v_cvt_pk_bf16_f32 v78, v72, v73
	v_cvt_pk_bf16_f32 v79, v74, v75
	v_cvt_pk_bf16_f32 v68, v68, v69
	v_cvt_pk_bf16_f32 v69, v70, v71
	v_cvt_pk_bf16_f32 v70, v64, v65
	v_cvt_pk_bf16_f32 v71, v66, v67
	s_not_b64 vcc, s[2:3]
	v_cndmask_b32_dpp v80, v92, v84, vcc row_ror:8 row_mask:0xf bank_mask:0xf
	v_cndmask_b32_dpp v81, v93, v85, vcc row_ror:8 row_mask:0xf bank_mask:0xf
	v_cndmask_b32_dpp v82, v94, v86, vcc row_ror:8 row_mask:0xf bank_mask:0xf
	v_cndmask_b32_dpp v83, v95, v87, vcc row_ror:8 row_mask:0xf bank_mask:0xf
	v_cndmask_b32_dpp v64, v76, v68, vcc row_ror:8 row_mask:0xf bank_mask:0xf
	v_cndmask_b32_dpp v65, v77, v69, vcc row_ror:8 row_mask:0xf bank_mask:0xf
	v_cndmask_b32_dpp v66, v78, v70, vcc row_ror:8 row_mask:0xf bank_mask:0xf
	v_cndmask_b32_dpp v67, v79, v71, vcc row_ror:8 row_mask:0xf bank_mask:0xf
	s_mov_b64 vcc, s[2:3]
	v_cndmask_b32_dpp v88, v84, v92, vcc row_ror:8 row_mask:0xf bank_mask:0xf
	v_cndmask_b32_dpp v89, v85, v93, vcc row_ror:8 row_mask:0xf bank_mask:0xf
	v_cndmask_b32_dpp v90, v86, v94, vcc row_ror:8 row_mask:0xf bank_mask:0xf
	v_cndmask_b32_dpp v91, v87, v95, vcc row_ror:8 row_mask:0xf bank_mask:0xf
	v_cndmask_b32_dpp v72, v68, v76, vcc row_ror:8 row_mask:0xf bank_mask:0xf
	v_cndmask_b32_dpp v73, v69, v77, vcc row_ror:8 row_mask:0xf bank_mask:0xf
	v_cndmask_b32_dpp v74, v70, v78, vcc row_ror:8 row_mask:0xf bank_mask:0xf
	v_cndmask_b32_dpp v75, v71, v79, vcc row_ror:8 row_mask:0xf bank_mask:0xf
	v_lshl_add_u64 v[164:165], v[166:167], 0, s[98:99]
	global_store_dwordx4 v[164:165], v[88:91], off nt
	v_lshl_add_u64 v[166:167], v[164:165], 0, s[98:99]
	global_store_dwordx4 v[166:167], v[80:83], off nt
	v_lshl_add_u64 v[164:165], v[166:167], 0, s[98:99]
; __device__ __forceinline__ unsigned cvt_pk_bf16(float lo, float hi) { const cvt_f32x2_t v = {lo, hi}; const cvt_bf16x2_t b = __builtin_convertvector(v, cvt_bf16x2_t); return __builtin_bit_cast(unsigned, b); }
; __device__ __forceinline__ unsigned swap8(unsigned v) { return (unsigned)__builtin_amdgcn_update_dpp(0, (int)v, 0x128  , 0xF, 0xF, false); }
; __device__ __forceinline__ void wide_store(bf16_t* O, int ldc, int rowg  , int col0  , int fr, u32x4 w0, u32x4 w1) {
;     const bool lo = fr < 8;
;     u32x4 snd = lo ? w1 : w0, rcv;
;     rcv.x = swap8(snd.x); rcv.y = swap8(snd.y); rcv.z = swap8(snd.z); rcv.w = swap8(snd.w);
;     const u32x4 first = lo ? w0 : rcv, second = lo ? rcv : w1;
;     bf16_t* p = O + (size_t)(rowg + (fr & 7)) * ldc + col0 + (lo ? 0 : 32);
;     __builtin_nontemporal_store(first, (u32x4*)p); __builtin_nontemporal_store(second, (u32x4*)(p + (size_t)8 * ldc));
; }
;     __device__ __forceinline__ void operator()(const f32x4 (&acc)[2][2][4][2], const Unit& u, int wr, int wc, int fr, int fq) const {
;         const int col0 = u.pn * BM + wc * 64 + 8 * fq;
; #pragma unroll
;         for (int ai = 0; ai < 2; ++ai)
; #pragma unroll
;             for (int m = 0; m < 4; ++m) { const int rowg = u.pm * BM + ai * HALF + wr * 64 + m * 16;
;                 const float sc = slots ? rstd_from_slots(slots, rowg + fr, fq) : 1.0f;
;                 u32x4 w[2];
; #pragma unroll
;                 for (int bj = 0; bj < 2; ++bj) { const f32x4 v0 = acc[ai][bj][m][0] * sc, v1 = acc[ai][bj][m][1] * sc;
;                     w[bj].x = cvt_pk_bf16(v0[0], v0[1]); w[bj].y = cvt_pk_bf16(v0[2], v0[3]); w[bj].z = cvt_pk_bf16(v1[0], v1[1]); w[bj].w = cvt_pk_bf16(v1[2], v1[3]); }
;                 wide_store(O, ldc, rowg, col0, fr, w[0], w[1]); }
	global_store_dwordx4 v[164:165], v[72:75], off nt
	v_lshl_add_u64 v[166:167], v[164:165], 0, s[98:99]
	global_store_dwordx4 v[166:167], v[64:67], off nt
	v_cvt_pk_bf16_f32 v60, v60, v61
	v_cvt_pk_bf16_f32 v61, v62, v63
	v_cvt_pk_bf16_f32 v62, v56, v57
	v_cvt_pk_bf16_f32 v63, v58, v59
	v_cvt_pk_bf16_f32 v52, v52, v53
	v_cvt_pk_bf16_f32 v53, v54, v55
	v_cvt_pk_bf16_f32 v54, v48, v49
	v_cvt_pk_bf16_f32 v55, v50, v51
	v_cvt_pk_bf16_f32 v44, v44, v45
	v_cvt_pk_bf16_f32 v45, v46, v47
	v_cvt_pk_bf16_f32 v46, v40, v41
	v_cvt_pk_bf16_f32 v47, v42, v43
	v_cvt_pk_bf16_f32 v36, v36, v37
	v_cvt_pk_bf16_f32 v37, v38, v39
	v_cvt_pk_bf16_f32 v38, v32, v33
	v_cvt_pk_bf16_f32 v39, v34, v35
	s_not_b64 vcc, s[2:3]
	v_cndmask_b32_dpp v48, v60, v52, vcc row_ror:8 row_mask:0xf bank_mask:0xf
	v_cndmask_b32_dpp v49, v61, v53, vcc row_ror:8 row_mask:0xf bank_mask:0xf
	v_cndmask_b32_dpp v50, v62, v54, vcc row_ror:8 row_mask:0xf bank_mask:0xf
	v_cndmask_b32_dpp v51, v63, v55, vcc row_ror:8 row_mask:0xf bank_mask:0xf
	v_cndmask_b32_dpp v32, v44, v36, vcc row_ror:8 row_mask:0xf bank_mask:0xf
	v_cndmask_b32_dpp v33, v45, v37, vcc row_ror:8 row_mask:0xf bank_mask:0xf
	v_cndmask_b32_dpp v34, v46, v38, vcc row_ror:8 row_mask:0xf bank_mask:0xf
	v_cndmask_b32_dpp v35, v47, v39, vcc row_ror:8 row_mask:0xf bank_mask:0xf
	s_mov_b64 vcc, s[2:3]
	v_cndmask_b32_dpp v56, v52, v60, vcc row_ror:8 row_mask:0xf bank_mask:0xf
	v_cndmask_b32_dpp v57, v53, v61, vcc row_ror:8 row_mask:0xf bank_mask:0xf
	v_cndmask_b32_dpp v58, v54, v62, vcc row_ror:8 row_mask:0xf bank_mask:0xf
	v_cndmask_b32_dpp v59, v55, v63, vcc row_ror:8 row_mask:0xf bank_mask:0xf
	v_cndmask_b32_dpp v40, v36, v44, vcc row_ror:8 row_mask:0xf bank_mask:0xf
	v_cndmask_b32_dpp v41, v37, v45, vcc row_ror:8 row_mask:0xf bank_mask:0xf
	v_cndmask_b32_dpp v42, v38, v46, vcc row_ror:8 row_mask:0xf bank_mask:0xf
	v_cndmask_b32_dpp v43, v39, v47, vcc row_ror:8 row_mask:0xf bank_mask:0xf
	s_mov_b32 s98, 0x144000
	v_lshl_add_u64 v[164:165], v[166:167], 0, s[98:99]
	s_mov_b32 s98, 0x24000
	global_store_dwordx4 v[164:165], v[56:59], off nt
	v_lshl_add_u64 v[166:167], v[164:165], 0, s[98:99]
	global_store_dwordx4 v[166:167], v[48:51], off nt
	v_lshl_add_u64 v[164:165], v[166:167], 0, s[98:99]
	global_store_dwordx4 v[164:165], v[40:43], off nt
	v_lshl_add_u64 v[166:167], v[164:165], 0, s[98:99]
	global_store_dwordx4 v[166:167], v[32:35], off nt
	v_cvt_pk_bf16_f32 v28, v28, v29
	v_cvt_pk_bf16_f32 v29, v30, v31
	v_cvt_pk_bf16_f32 v30, v24, v25
	v_cvt_pk_bf16_f32 v31, v26, v27
	v_cvt_pk_bf16_f32 v20, v20, v21
	v_cvt_pk_bf16_f32 v21, v22, v23
	v_cvt_pk_bf16_f32 v22, v16, v17
	v_cvt_pk_bf16_f32 v23, v18, v19
	v_cvt_pk_bf16_f32 v12, v12, v13
	v_cvt_pk_bf16_f32 v13, v14, v15
	v_cvt_pk_bf16_f32 v14, v8, v9
	v_cvt_pk_bf16_f32 v15, v10, v11
	v_cvt_pk_bf16_f32 v4, v4, v5
	v_cvt_pk_bf16_f32 v5, v6, v7
	v_cvt_pk_bf16_f32 v6, v0, v1
	v_cvt_pk_bf16_f32 v7, v2, v3
	s_not_b64 vcc, s[2:3]
	v_cndmask_b32_dpp v16, v28, v20, vcc row_ror:8 row_mask:0xf bank_mask:0xf
	v_cndmask_b32_dpp v17, v29, v21, vcc row_ror:8 row_mask:0xf bank_mask:0xf
	v_cndmask_b32_dpp v18, v30, v22, vcc row_ror:8 row_mask:0xf bank_mask:0xf
	v_cndmask_b32_dpp v19, v31, v23, vcc row_ror:8 row_mask:0xf bank_mask:0xf
	v_cndmask_b32_dpp v0, v12, v4, vcc row_ror:8 row_mask:0xf bank_mask:0xf
	v_cndmask_b32_dpp v1, v13, v5, vcc row_ror:8 row_mask:0xf bank_mask:0xf
	v_cndmask_b32_dpp v2, v14, v6, vcc row_ror:8 row_mask:0xf bank_mask:0xf
	v_cndmask_b32_dpp v3, v15, v7, vcc row_ror:8 row_mask:0xf bank_mask:0xf
	s_mov_b64 vcc, s[2:3]
	v_cndmask_b32_dpp v24, v20, v28, vcc row_ror:8 row_mask:0xf bank_mask:0xf
	v_cndmask_b32_dpp v25, v21, v29, vcc row_ror:8 row_mask:0xf bank_mask:0xf
	v_cndmask_b32_dpp v26, v22, v30, vcc row_ror:8 row_mask:0xf bank_mask:0xf
	v_cndmask_b32_dpp v27, v23, v31, vcc row_ror:8 row_mask:0xf bank_mask:0xf
	v_cndmask_b32_dpp v8, v4, v12, vcc row_ror:8 row_mask:0xf bank_mask:0xf
	v_cndmask_b32_dpp v9, v5, v13, vcc row_ror:8 row_mask:0xf bank_mask:0xf
	v_cndmask_b32_dpp v10, v6, v14, vcc row_ror:8 row_mask:0xf bank_mask:0xf
	v_cndmask_b32_dpp v11, v7, v15, vcc row_ror:8 row_mask:0xf bank_mask:0xf
	v_lshl_add_u64 v[164:165], v[166:167], 0, s[98:99]
	global_store_dwordx4 v[164:165], v[24:27], off nt
	v_lshl_add_u64 v[166:167], v[164:165], 0, s[98:99]
	global_store_dwordx4 v[166:167], v[16:19], off nt
	v_lshl_add_u64 v[164:165], v[166:167], 0, s[98:99]
	global_store_dwordx4 v[164:165], v[8:11], off nt
	v_lshl_add_u64 v[166:167], v[164:165], 0, s[98:99]
	global_store_dwordx4 v[166:167], v[0:3], off nt
	s_andn2_b64 vcc, exec, s[4:5]
	s_mov_b64 s[0:1], -1
	s_cbranch_vccnz .LBB0_211
	s_andn2_b64 vcc, exec, s[8:9]
	s_cbranch_vccnz .LBB0_210
	s_barrier
	s_branch .LBB0_210

; __device__ __forceinline__ unsigned cvt_pk_bf16(float lo, float hi) { const cvt_f32x2_t v = {lo, hi}; const cvt_bf16x2_t b = __builtin_convertvector(v, cvt_bf16x2_t); return __builtin_bit_cast(unsigned, b); }
; __device__ __forceinline__ unsigned swap8(unsigned v) { return (unsigned)__builtin_amdgcn_update_dpp(0, (int)v, 0x128  , 0xF, 0xF, false); }
; __device__ __forceinline__ void wide_store(bf16_t* O, int ldc, int rowg  , int col0  , int fr, u32x4 w0, u32x4 w1) {
;     const bool lo = fr < 8;
;     u32x4 snd = lo ? w1 : w0, rcv;
;     rcv.x = swap8(snd.x); rcv.y = swap8(snd.y); rcv.z = swap8(snd.z); rcv.w = swap8(snd.w);
;     const u32x4 first = lo ? w0 : rcv, second = lo ? rcv : w1;
;     bf16_t* p = O + (size_t)(rowg + (fr & 7)) * ldc + col0 + (lo ? 0 : 32);
;     __builtin_nontemporal_store(first, (u32x4*)p); __builtin_nontemporal_store(second, (u32x4*)(p + (size_t)8 * ldc));
; }
;     __device__ __forceinline__ void operator()(const f32x4 (&acc)[2][2][4][2], const Unit& u, int wr, int wc, int fr, int fq) const {
;         const int col0 = u.pn * BM + wc * 64 + 8 * fq;
; #pragma unroll
;         for (int ai = 0; ai < 2; ++ai)
; #pragma unroll
;             for (int m = 0; m < 4; ++m) { const int rowg = u.pm * BM + ai * HALF + wr * 64 + m * 16;
;                 const float sc = slots ? rstd_from_slots(slots, rowg + fr, fq) : 1.0f;
;                 u32x4 w[2];
; #pragma unroll
;                 for (int bj = 0; bj < 2; ++bj) { const f32x4 v0 = acc[ai][bj][m][0] * sc, v1 = acc[ai][bj][m][1] * sc;
;                     w[bj].x = cvt_pk_bf16(v0[0], v0[1]); w[bj].y = cvt_pk_bf16(v0[2], v0[3]); w[bj].z = cvt_pk_bf16(v1[0], v1[1]); w[bj].w = cvt_pk_bf16(v1[2], v1[3]); }
;                 wide_store(O, ldc, rowg, col0, fr, w[0], w[1]); }
.LBB0_372:
	v_readlane_b32 s30, v239, 49
	v_readlane_b32 s31, v239, 50
	s_lshl_b32 s0, s0, 8
	v_lshl_or_b32 v162, s1, 8, v147
	v_add_u32_e32 v164, s0, v148
	v_ashrrev_i32_e32 v163, 31, v162
	s_mov_b32 s98, 0x24000
	s_mov_b32 s99, 0
	v_lshlrev_b64 v[162:163], 1, v[162:163]
	v_mov_b64_e32 v[168:169], s[30:31]
	v_mad_i64_i32 v[164:165], s[20:21], v164, s55, v[168:169]
	v_lshl_add_u64 v[162:163], v[162:163], 0, v[136:137]
	v_lshl_add_u64 v[164:165], v[164:165], 0, v[162:163]
	v_cvt_pk_bf16_f32 v124, v124, v125
	v_cvt_pk_bf16_f32 v125, v126, v127
	v_cvt_pk_bf16_f32 v126, v120, v121
	v_cvt_pk_bf16_f32 v127, v122, v123
	v_cvt_pk_bf16_f32 v116, v116, v117
	v_cvt_pk_bf16_f32 v117, v118, v119
	v_cvt_pk_bf16_f32 v118, v112, v113
	v_cvt_pk_bf16_f32 v119, v114, v115
	v_cvt_pk_bf16_f32 v108, v108, v109
	v_cvt_pk_bf16_f32 v109, v110, v111
	v_cvt_pk_bf16_f32 v110, v104, v105
	v_cvt_pk_bf16_f32 v111, v106, v107
	v_cvt_pk_bf16_f32 v100, v100, v101
	v_cvt_pk_bf16_f32 v101, v102, v103
	v_cvt_pk_bf16_f32 v102, v96, v97
	v_cvt_pk_bf16_f32 v103, v98, v99
	s_not_b64 vcc, s[2:3]
	v_cndmask_b32_dpp v112, v124, v116, vcc row_ror:8 row_mask:0xf bank_mask:0xf
	v_cndmask_b32_dpp v113, v125, v117, vcc row_ror:8 row_mask:0xf bank_mask:0xf
	v_cndmask_b32_dpp v114, v126, v118, vcc row_ror:8 row_mask:0xf bank_mask:0xf
	v_cndmask_b32_dpp v115, v127, v119, vcc row_ror:8 row_mask:0xf bank_mask:0xf
	v_cndmask_b32_dpp v96, v108, v100, vcc row_ror:8 row_mask:0xf bank_mask:0xf
	v_cndmask_b32_dpp v97, v109, v101, vcc row_ror:8 row_mask:0xf bank_mask:0xf
	v_cndmask_b32_dpp v98, v110, v102, vcc row_ror:8 row_mask:0xf bank_mask:0xf
	v_cndmask_b32_dpp v99, v111, v103, vcc row_ror:8 row_mask:0xf bank_mask:0xf
	s_mov_b64 vcc, s[2:3]
	v_cndmask_b32_dpp v120, v116, v124, vcc row_ror:8 row_mask:0xf bank_mask:0xf
	v_cndmask_b32_dpp v121, v117, v125, vcc row_ror:8 row_mask:0xf bank_mask:0xf
	v_cndmask_b32_dpp v122, v118, v126, vcc row_ror:8 row_mask:0xf bank_mask:0xf
	v_cndmask_b32_dpp v123, v119, v127, vcc row_ror:8 row_mask:0xf bank_mask:0xf
	v_cndmask_b32_dpp v104, v100, v108, vcc row_ror:8 row_mask:0xf bank_mask:0xf
	v_cndmask_b32_dpp v105, v101, v109, vcc row_ror:8 row_mask:0xf bank_mask:0xf
	v_cndmask_b32_dpp v106, v102, v110, vcc row_ror:8 row_mask:0xf bank_mask:0xf
	v_cndmask_b32_dpp v107, v103, v111, vcc row_ror:8 row_mask:0xf bank_mask:0xf
	global_store_dwordx4 v[164:165], v[120:123], off nt
	v_lshl_add_u64 v[166:167], v[164:165], 0, s[98:99]
	global_store_dwordx4 v[166:167], v[112:115], off nt
	v_lshl_add_u64 v[164:165], v[166:167], 0, s[98:99]
	global_store_dwordx4 v[164:165], v[104:107], off nt
	v_lshl_add_u64 v[166:167], v[164:165], 0, s[98:99]
	global_store_dwordx4 v[166:167], v[96:99], off nt
	v_cvt_pk_bf16_f32 v92, v92, v93
	v_cvt_pk_bf16_f32 v93, v94, v95
	v_cvt_pk_bf16_f32 v94, v88, v89
	v_cvt_pk_bf16_f32 v95, v90, v91
	v_cvt_pk_bf16_f32 v84, v84, v85
	v_cvt_pk_bf16_f32 v85, v86, v87
	v_cvt_pk_bf16_f32 v86, v80, v81
	v_cvt_pk_bf16_f32 v87, v82, v83
	v_cvt_pk_bf16_f32 v76, v76, v77
	v_cvt_pk_bf16_f32 v77, v78, v79
	v_cvt_pk_bf16_f32 v78, v72, v73
	v_cvt_pk_bf16_f32 v79, v74, v75
	v_cvt_pk_bf16_f32 v68, v68, v69
	v_cvt_pk_bf16_f32 v69, v70, v71
	v_cvt_pk_bf16_f32 v70, v64, v65
	v_cvt_pk_bf16_f32 v71, v66, v67
	s_not_b64 vcc, s[2:3]
	v_cndmask_b32_dpp v80, v92, v84, vcc row_ror:8 row_mask:0xf bank_mask:0xf
	v_cndmask_b32_dpp v81, v93, v85, vcc row_ror:8 row_mask:0xf bank_mask:0xf
	v_cndmask_b32_dpp v82, v94, v86, vcc row_ror:8 row_mask:0xf bank_mask:0xf
	v_cndmask_b32_dpp v83, v95, v87, vcc row_ror:8 row_mask:0xf bank_mask:0xf
	v_cndmask_b32_dpp v64, v76, v68, vcc row_ror:8 row_mask:0xf bank_mask:0xf
	v_cndmask_b32_dpp v65, v77, v69, vcc row_ror:8 row_mask:0xf bank_mask:0xf
	v_cndmask_b32_dpp v66, v78, v70, vcc row_ror:8 row_mask:0xf bank_mask:0xf
	v_cndmask_b32_dpp v67, v79, v71, vcc row_ror:8 row_mask:0xf bank_mask:0xf
	s_mov_b64 vcc, s[2:3]
	v_cndmask_b32_dpp v88, v84, v92, vcc row_ror:8 row_mask:0xf bank_mask:0xf
	v_cndmask_b32_dpp v89, v85, v93, vcc row_ror:8 row_mask:0xf bank_mask:0xf
	v_cndmask_b32_dpp v90, v86, v94, vcc row_ror:8 row_mask:0xf bank_mask:0xf
	v_cndmask_b32_dpp v91, v87, v95, vcc row_ror:8 row_mask:0xf bank_mask:0xf
	v_cndmask_b32_dpp v72, v68, v76, vcc row_ror:8 row_mask:0xf bank_mask:0xf
	v_cndmask_b32_dpp v73, v69, v77, vcc row_ror:8 row_mask:0xf bank_mask:0xf
	v_cndmask_b32_dpp v74, v70, v78, vcc row_ror:8 row_mask:0xf bank_mask:0xf
	v_cndmask_b32_dpp v75, v71, v79, vcc row_ror:8 row_mask:0xf bank_mask:0xf
	v_lshl_add_u64 v[164:165], v[166:167], 0, s[98:99]
	global_store_dwordx4 v[164:165], v[88:91], off nt
	v_lshl_add_u64 v[166:167], v[164:165], 0, s[98:99]
	global_store_dwordx4 v[166:167], v[80:83], off nt
	v_lshl_add_u64 v[164:165], v[166:167], 0, s[98:99]
; __device__ __forceinline__ unsigned cvt_pk_bf16(float lo, float hi) { const cvt_f32x2_t v = {lo, hi}; const cvt_bf16x2_t b = __builtin_convertvector(v, cvt_bf16x2_t); return __builtin_bit_cast(unsigned, b); }
; __device__ __forceinline__ unsigned swap8(unsigned v) { return (unsigned)__builtin_amdgcn_update_dpp(0, (int)v, 0x128  , 0xF, 0xF, false); }
; __device__ __forceinline__ void wide_store(bf16_t* O, int ldc, int rowg  , int col0  , int fr, u32x4 w0, u32x4 w1) {
;     const bool lo = fr < 8;
;     u32x4 snd = lo ? w1 : w0, rcv;
;     rcv.x = swap8(snd.x); rcv.y = swap8(snd.y); rcv.z = swap8(snd.z); rcv.w = swap8(snd.w);
;     const u32x4 first = lo ? w0 : rcv, second = lo ? rcv : w1;
;     bf16_t* p = O + (size_t)(rowg + (fr & 7)) * ldc + col0 + (lo ? 0 : 32);
;     __builtin_nontemporal_store(first, (u32x4*)p); __builtin_nontemporal_store(second, (u32x4*)(p + (size_t)8 * ldc));
; }
;     __device__ __forceinline__ void operator()(const f32x4 (&acc)[2][2][4][2], const Unit& u, int wr, int wc, int fr, int fq) const {
;         const int col0 = u.pn * BM + wc * 64 + 8 * fq;
; #pragma unroll
;         for (int ai = 0; ai < 2; ++ai)
; #pragma unroll
;             for (int m = 0; m < 4; ++m) { const int rowg = u.pm * BM + ai * HALF + wr * 64 + m * 16;
;                 const float sc = slots ? rstd_from_slots(slots, rowg + fr, fq) : 1.0f;
;                 u32x4 w[2];
; #pragma unroll
;                 for (int bj = 0; bj < 2; ++bj) { const f32x4 v0 = acc[ai][bj][m][0] * sc, v1 = acc[ai][bj][m][1] * sc;
;                     w[bj].x = cvt_pk_bf16(v0[0], v0[1]); w[bj].y = cvt_pk_bf16(v0[2], v0[3]); w[bj].z = cvt_pk_bf16(v1[0], v1[1]); w[bj].w = cvt_pk_bf16(v1[2], v1[3]); }
;                 wide_store(O, ldc, rowg, col0, fr, w[0], w[1]); }
	global_store_dwordx4 v[164:165], v[72:75], off nt
	v_lshl_add_u64 v[166:167], v[164:165], 0, s[98:99]
	global_store_dwordx4 v[166:167], v[64:67], off nt
	v_cvt_pk_bf16_f32 v60, v60, v61
	v_cvt_pk_bf16_f32 v61, v62, v63
	v_cvt_pk_bf16_f32 v62, v56, v57
	v_cvt_pk_bf16_f32 v63, v58, v59
	v_cvt_pk_bf16_f32 v52, v52, v53
	v_cvt_pk_bf16_f32 v53, v54, v55
	v_cvt_pk_bf16_f32 v54, v48, v49
	v_cvt_pk_bf16_f32 v55, v50, v51
	v_cvt_pk_bf16_f32 v44, v44, v45
	v_cvt_pk_bf16_f32 v45, v46, v47
	v_cvt_pk_bf16_f32 v46, v40, v41
	v_cvt_pk_bf16_f32 v47, v42, v43
	v_cvt_pk_bf16_f32 v36, v36, v37
	v_cvt_pk_bf16_f32 v37, v38, v39
	v_cvt_pk_bf16_f32 v38, v32, v33
	v_cvt_pk_bf16_f32 v39, v34, v35
	s_not_b64 vcc, s[2:3]
	v_cndmask_b32_dpp v48, v60, v52, vcc row_ror:8 row_mask:0xf bank_mask:0xf
	v_cndmask_b32_dpp v49, v61, v53, vcc row_ror:8 row_mask:0xf bank_mask:0xf
	v_cndmask_b32_dpp v50, v62, v54, vcc row_ror:8 row_mask:0xf bank_mask:0xf
	v_cndmask_b32_dpp v51, v63, v55, vcc row_ror:8 row_mask:0xf bank_mask:0xf
	v_cndmask_b32_dpp v32, v44, v36, vcc row_ror:8 row_mask:0xf bank_mask:0xf
	v_cndmask_b32_dpp v33, v45, v37, vcc row_ror:8 row_mask:0xf bank_mask:0xf
	v_cndmask_b32_dpp v34, v46, v38, vcc row_ror:8 row_mask:0xf bank_mask:0xf
	v_cndmask_b32_dpp v35, v47, v39, vcc row_ror:8 row_mask:0xf bank_mask:0xf
	s_mov_b64 vcc, s[2:3]
	v_cndmask_b32_dpp v56, v52, v60, vcc row_ror:8 row_mask:0xf bank_mask:0xf
	v_cndmask_b32_dpp v57, v53, v61, vcc row_ror:8 row_mask:0xf bank_mask:0xf
	v_cndmask_b32_dpp v58, v54, v62, vcc row_ror:8 row_mask:0xf bank_mask:0xf
	v_cndmask_b32_dpp v59, v55, v63, vcc row_ror:8 row_mask:0xf bank_mask:0xf
	v_cndmask_b32_dpp v40, v36, v44, vcc row_ror:8 row_mask:0xf bank_mask:0xf
	v_cndmask_b32_dpp v41, v37, v45, vcc row_ror:8 row_mask:0xf bank_mask:0xf
	v_cndmask_b32_dpp v42, v38, v46, vcc row_ror:8 row_mask:0xf bank_mask:0xf
	v_cndmask_b32_dpp v43, v39, v47, vcc row_ror:8 row_mask:0xf bank_mask:0xf
	s_mov_b32 s98, 0x144000
	v_lshl_add_u64 v[164:165], v[166:167], 0, s[98:99]
	s_mov_b32 s98, 0x24000
	global_store_dwordx4 v[164:165], v[56:59], off nt
	v_lshl_add_u64 v[166:167], v[164:165], 0, s[98:99]
	global_store_dwordx4 v[166:167], v[48:51], off nt
	v_lshl_add_u64 v[164:165], v[166:167], 0, s[98:99]
	global_store_dwordx4 v[164:165], v[40:43], off nt
	v_lshl_add_u64 v[166:167], v[164:165], 0, s[98:99]
	global_store_dwordx4 v[166:167], v[32:35], off nt
	v_cvt_pk_bf16_f32 v28, v28, v29
	v_cvt_pk_bf16_f32 v29, v30, v31
	v_cvt_pk_bf16_f32 v30, v24, v25
	v_cvt_pk_bf16_f32 v31, v26, v27
	v_cvt_pk_bf16_f32 v20, v20, v21
	v_cvt_pk_bf16_f32 v21, v22, v23
	v_cvt_pk_bf16_f32 v22, v16, v17
	v_cvt_pk_bf16_f32 v23, v18, v19
	v_cvt_pk_bf16_f32 v12, v12, v13
	v_cvt_pk_bf16_f32 v13, v14, v15
	v_cvt_pk_bf16_f32 v14, v8, v9
	v_cvt_pk_bf16_f32 v15, v10, v11
	v_cvt_pk_bf16_f32 v4, v4, v5
	v_cvt_pk_bf16_f32 v5, v6, v7
	v_cvt_pk_bf16_f32 v6, v0, v1
	v_cvt_pk_bf16_f32 v7, v2, v3
	s_not_b64 vcc, s[2:3]
	v_cndmask_b32_dpp v16, v28, v20, vcc row_ror:8 row_mask:0xf bank_mask:0xf
	v_cndmask_b32_dpp v17, v29, v21, vcc row_ror:8 row_mask:0xf bank_mask:0xf
	v_cndmask_b32_dpp v18, v30, v22, vcc row_ror:8 row_mask:0xf bank_mask:0xf
	v_cndmask_b32_dpp v19, v31, v23, vcc row_ror:8 row_mask:0xf bank_mask:0xf
	v_cndmask_b32_dpp v0, v12, v4, vcc row_ror:8 row_mask:0xf bank_mask:0xf
	v_cndmask_b32_dpp v1, v13, v5, vcc row_ror:8 row_mask:0xf bank_mask:0xf
	v_cndmask_b32_dpp v2, v14, v6, vcc row_ror:8 row_mask:0xf bank_mask:0xf
	v_cndmask_b32_dpp v3, v15, v7, vcc row_ror:8 row_mask:0xf bank_mask:0xf
	s_mov_b64 vcc, s[2:3]
	v_cndmask_b32_dpp v24, v20, v28, vcc row_ror:8 row_mask:0xf bank_mask:0xf
	v_cndmask_b32_dpp v25, v21, v29, vcc row_ror:8 row_mask:0xf bank_mask:0xf
	v_cndmask_b32_dpp v26, v22, v30, vcc row_ror:8 row_mask:0xf bank_mask:0xf
	v_cndmask_b32_dpp v27, v23, v31, vcc row_ror:8 row_mask:0xf bank_mask:0xf
	v_cndmask_b32_dpp v8, v4, v12, vcc row_ror:8 row_mask:0xf bank_mask:0xf
	v_cndmask_b32_dpp v9, v5, v13, vcc row_ror:8 row_mask:0xf bank_mask:0xf
	v_cndmask_b32_dpp v10, v6, v14, vcc row_ror:8 row_mask:0xf bank_mask:0xf
	v_cndmask_b32_dpp v11, v7, v15, vcc row_ror:8 row_mask:0xf bank_mask:0xf
	v_lshl_add_u64 v[164:165], v[166:167], 0, s[98:99]
	global_store_dwordx4 v[164:165], v[24:27], off nt
	v_lshl_add_u64 v[166:167], v[164:165], 0, s[98:99]
	global_store_dwordx4 v[166:167], v[16:19], off nt
	v_lshl_add_u64 v[164:165], v[166:167], 0, s[98:99]
	global_store_dwordx4 v[164:165], v[8:11], off nt
	v_lshl_add_u64 v[166:167], v[164:165], 0, s[98:99]
	global_store_dwordx4 v[166:167], v[0:3], off nt
	s_andn2_b64 vcc, exec, s[4:5]
	s_mov_b64 s[0:1], -1
	s_cbranch_vccnz .LBB0_365
	s_andn2_b64 vcc, exec, s[8:9]
	s_cbranch_vccnz .LBB0_364
	s_barrier
	s_branch .LBB0_364
